# P2 work queues: after a failed pop, one 8-lane peek of all queue counters; queues already empty are skipped instead of popped one by one
# baseline (speedup 1.0000x reference)
; __device__ __forceinline__ void p2_mixers(Frame& F, const Args& A) {
;     ...
; #pragma unroll 1
;     for (int qq = 0; qq < 8; ++qq) {
;         const int q = (myq + qq) & 7;
;         for (;;) {
;             if (threadIdx.x == 0) F.MISC[0] = __hip_atomic_fetch_add(F.ctl + CW_QUEUE + 64 * q, 1u, RLX_AGENT);
;             __syncthreads();
;             const int k = (int)F.MISC[0];
;             __syncthreads();
;             if (k >= NU_Q) break;
.LBB0_642:
	s_and_saveexec_b64 s[2:3], s[84:85]
	s_cbranch_execz .Lq_peek_skip
	v_readlane_b32 s4, v251, 4
	v_readlane_b32 s5, v251, 5
	s_mov_b64 exec, 0xff
	v_mbcnt_lo_u32_b32 v1, -1, 0
	v_lshlrev_b32_e32 v1, 8, v1
	s_nop 1
	global_load_dword v2, v1, s[4:5] offset:256 sc1
	s_waitcnt vmcnt(0)
	v_cmp_lt_u32_e32 vcc, 0x6f, v2
	s_nop 1
	s_and_b32 s6, vcc_lo, 0xff
	s_mov_b64 exec, 1
	v_mov_b32_e32 v1, s6
	v_mov_b32_e32 v2, s90
	s_nop 0
	ds_write_b32 v2, v1 offset:4
.Lq_peek_skip:
	s_or_b64 exec, exec, s[2:3]
	s_waitcnt lgkmcnt(0)
	s_barrier
	ds_read_b32 v1, v213 offset:4
	s_waitcnt lgkmcnt(0)
	v_readfirstlane_b32 s6, v1
	v_readlane_b32 s3, v250, 48
	v_readlane_b32 s7, v250, 37
.Lq_next:
	s_add_i32 s3, s3, 1
	s_cmp_lg_u32 s3, 8
	s_cbranch_scc0 .LBB0_807
	s_add_i32 s2, s3, s7
	s_and_b32 s2, s2, 7
	s_lshr_b32 s2, s6, s2
	s_and_b32 s2, s2, 1
	s_cmp_eq_u32 s2, 1
	s_cbranch_scc1 .Lq_next
